# v072 + GDN scan finalizer waves issue their LDS-DMA tile loads right after the step barrier (before the finalize math), counted vmcnt
# baseline (speedup 1.0000x reference)
.LBB0_443:
	s_and_b64 vcc, exec, s[24:25]
	s_cbranch_vccnz .Lscan_top_w0
	s_waitcnt vmcnt(12)
	s_branch .Lscan_top_w1

.Lscan_top_w1:
	s_waitcnt lgkmcnt(0)
	s_barrier
	s_andn2_b64 vcc, exec, s[22:23]
	s_cbranch_vccnz .LBB0_445
	s_add_i32 s58, s29, 1
	s_cmpk_lg_i32 s56, 0xfc0
	s_cselect_b32 s31, s58, 63
	s_add_u32 s38, s34, s31
	v_mov_b32_e32 v106, v180
	s_addc_u32 s39, s35, 0
	s_bitcmp1_b32 s57, 0
	v_ashrrev_i32_e32 v107, 4, v106
	v_add_u32_e32 v2, s52, v107
	s_cselect_b32 s0, 0xe000, 0
	v_xor_b32_e32 v4, v2, v106
	s_add_i32 s37, s27, s0
	v_ashrrev_i32_e32 v108, 3, v106
	s_lshl_b64 s[0:1], s[38:39], 13
	s_lshl_b64 s[60:61], s[38:39], 14
	v_lshlrev_b32_e32 v2, 7, v2
	v_lshlrev_b32_e32 v4, 3, v4
	s_add_u32 s62, s43, s60
	v_and_or_b32 v2, v4, s50, v2
	v_add_u32_e32 v4, s53, v108
	s_addc_u32 s63, s44, s61
	v_lshrrev_b32_e32 v5, 1, v4
	s_add_u32 s64, s15, s60
	v_xor_b32_e32 v5, v5, v106
	s_addc_u32 s65, s19, s61
	s_add_i32 s59, s37, 0x4000
	v_lshlrev_b32_e32 v4, 6, v4
	v_lshlrev_b32_e32 v5, 3, v5
	v_lshlrev_b64 v[102:103], 1, v[2:3]
	s_add_u32 s60, s45, s60
	v_and_or_b32 v4, v5, 56, v4
	v_lshl_add_u64 v[104:105], s[62:63], 0, v[102:103]
	s_mov_b32 m0, s37
	v_mov_b32_e32 v5, v3
	s_addc_u32 s61, s46, s61
	s_add_i32 s66, s37, 0x8000
	global_load_lds_dwordx4 v[104:105], off
	v_lshl_add_u64 v[102:103], s[64:65], 0, v[102:103]
	s_mov_b32 m0, s59
	v_lshlrev_b64 v[4:5], 1, v[4:5]
	global_load_lds_dwordx4 v[102:103], off
	v_lshl_add_u64 v[102:103], s[60:61], 0, v[4:5]
	s_mov_b32 m0, s66
	v_add_u32_e32 v2, s54, v107
	global_load_lds_dwordx4 v[102:103], off
	v_xor_b32_e32 v102, v2, v106
	v_lshlrev_b32_e32 v2, 7, v2
	v_lshlrev_b32_e32 v102, 3, v102
	v_and_or_b32 v2, v102, s50, v2
	v_add_u32_e32 v102, s55, v108
	v_lshrrev_b32_e32 v103, 1, v102
	v_lshlrev_b64 v[104:105], 1, v[2:3]
	v_xor_b32_e32 v103, v103, v106
	v_lshl_add_u64 v[106:107], s[62:63], 0, v[104:105]
	s_add_i32 m0, s37, 0x2000
	v_lshlrev_b32_e32 v102, 6, v102
	v_lshlrev_b32_e32 v103, 3, v103
	global_load_lds_dwordx4 v[106:107], off
	v_lshl_add_u64 v[104:105], s[64:65], 0, v[104:105]
	s_add_i32 m0, s37, 0x6000
	v_and_or_b32 v102, v103, 56, v102
	global_load_lds_dwordx4 v[104:105], off
	v_mov_b32_e32 v103, v3
	s_add_i32 m0, s37, 0xa000
	v_lshl_add_u64 v[102:103], v[102:103], 1, s[60:61]
	s_add_u32 s0, s33, s0
	global_load_lds_dwordx4 v[102:103], off
	s_addc_u32 s1, s40, s1
	s_add_i32 m0, s37, 0xc000
	v_lshl_add_u64 v[4:5], s[0:1], 0, v[4:5]
	global_load_lds_dwordx4 v[4:5], off
	s_min_u32 s0, s29, 1
	s_sub_i32 s1, s29, s0
	s_lshl_b32 s0, s0, 6
	v_subrev_u32_e32 v2, s0, v203
	s_and_b32 s0, s1, 1
	v_lshl_add_u32 v205, s0, 10, v199
	ds_read2_b32 v[4:5], v205 offset1:16
	ds_read2_b32 v[120:121], v205 offset0:128 offset1:144
	ds_read2_b32 v[122:123], v205 offset0:64 offset1:80
	ds_read2_b32 v[134:135], v205 offset0:192 offset1:208
	v_lshl_add_u32 v204, s0, 14, v182
	s_waitcnt lgkmcnt(0)
	v_mov_b32_e32 v102, v4
	v_mov_b32_e32 v103, v120
	v_mov_b32_e32 v104, v122
	v_mov_b32_e32 v105, v134
	v_add_u32_e32 v4, v204, v186
	s_waitcnt vmcnt(11)
	v_lshlrev_b32_e32 v114, 16, v170
	v_pk_add_f32 v[136:137], v[102:103], v[104:105]
	ds_read_b128 v[116:119], v4
	ds_read_b128 v[102:105], v183
	v_and_b32_e32 v115, 0xffff0000, v170
	ds_read_b128 v[106:109], v183 offset:16
	v_add_u32_e32 v4, v204, v188
	ds_read_b128 v[110:113], v4
	s_waitcnt lgkmcnt(3)
	v_lshlrev_b32_e32 v206, 16, v116
	v_lshlrev_b32_e32 v124, 16, v171
	v_and_b32_e32 v125, 0xffff0000, v171
	v_and_b32_e32 v207, 0xffff0000, v116
	v_lshlrev_b32_e32 v128, 16, v168
	v_and_b32_e32 v129, 0xffff0000, v168
	v_lshlrev_b32_e32 v168, 16, v169
	v_lshlrev_b32_e32 v126, 16, v118
	v_and_b32_e32 v127, 0xffff0000, v118
	v_and_b32_e32 v169, 0xffff0000, v169
	v_mov_b32_e32 v120, v5
	v_mov_b32_e32 v134, v123
	v_mov_b64_e32 v[132:133], v[128:129]
	v_lshlrev_b32_e32 v130, 16, v119
	v_and_b32_e32 v131, 0xffff0000, v119
	v_pk_add_f32 v[118:119], v[120:121], v[134:135]
	v_mov_b32_e32 v121, v136
	v_mov_b32_e32 v120, v118
	v_mov_b32_e32 v136, v119
	v_pk_add_f32 v[118:119], v[120:121], v[136:137]
	v_mov_b64_e32 v[122:123], s[18:19]
	v_pk_fma_f32 v[134:135], v[118:119], s[14:15], v[122:123] op_sel_hi:[1,0,0]
	v_add_u32_e32 v4, s56, v2
	v_mul_f32_e32 v2, 0x4b800000, v135
	v_cmp_gt_f32_e32 vcc, s51, v135
	v_ashrrev_i32_e32 v5, 31, v4
	v_lshlrev_b64 v[118:119], 11, v[4:5]
	v_cndmask_b32_e32 v2, v135, v2, vcc
	v_rsq_f32_e32 v2, v2
	v_mov_b64_e32 v[128:129], v[168:169]
	v_lshlrev_b32_e32 v116, 16, v117
	v_and_b32_e32 v117, 0xffff0000, v117
	v_mul_f32_e32 v5, 0x45800000, v2
	v_cndmask_b32_e32 v2, v2, v5, vcc
	v_pk_mul_f32 v[168:169], v[2:3], v[206:207] op_sel_hi:[0,1]
	s_waitcnt lgkmcnt(2)
	v_pk_mul_f32 v[168:169], v[102:103], v[168:169]
	v_cmp_gt_f32_e32 vcc, s51, v134
	v_pk_mul_f32 v[114:115], v[114:115], v[168:169]
	v_lshl_add_u64 v[136:137], v[150:151], 0, v[118:119]
	v_cvt_pk_bf16_f32 v168, v114, v115
	v_pk_mul_f32 v[114:115], v[2:3], v[116:117] op_sel_hi:[0,1]
	v_pk_mul_f32 v[114:115], v[104:105], v[114:115]
	ds_read_b128 v[118:121], v183
	v_pk_mul_f32 v[114:115], v[124:125], v[114:115]
	v_pk_mul_f32 v[124:125], v[2:3], v[126:127] op_sel_hi:[0,1]
	s_waitcnt lgkmcnt(2)
	v_pk_mul_f32 v[124:125], v[106:107], v[124:125]
	v_cvt_pk_bf16_f32 v169, v114, v115
	v_pk_mul_f32 v[124:125], v[132:133], v[124:125]
	ds_read_b128 v[114:117], v183 offset:16
	v_cvt_pk_bf16_f32 v170, v124, v125
	v_pk_mul_f32 v[124:125], v[2:3], v[130:131] op_sel_hi:[0,1]
	v_mul_f32_e32 v2, 0x4b800000, v134
	v_cndmask_b32_e32 v2, v134, v2, vcc
	v_rsq_f32_e32 v2, v2
	v_pk_mul_f32 v[124:125], v[108:109], v[124:125]
	v_mul_f32_e32 v5, 0x45800000, v2
	v_pk_mul_f32 v[124:125], v[128:129], v[124:125]
	v_cndmask_b32_e32 v2, v2, v5, vcc
	v_cvt_pk_bf16_f32 v171, v124, v125
	v_lshlrev_b32_e32 v124, 16, v164
	v_and_b32_e32 v125, 0xffff0000, v164
	s_waitcnt lgkmcnt(2)
	v_lshlrev_b32_e32 v128, 16, v110
	v_and_b32_e32 v129, 0xffff0000, v110
	v_pk_mul_f32 v[128:129], v[2:3], v[128:129] op_sel_hi:[0,1]
	v_pk_mul_f32 v[128:129], v[102:103], v[128:129]
	v_mov_b64_e32 v[52:53], v[168:169]
	v_mov_b64_e32 v[54:55], v[170:171]
	v_mov_b64_e32 v[56:57], v[136:137]
	v_pk_mul_f32 v[124:125], v[124:125], v[128:129]
	v_lshlrev_b32_e32 v128, 16, v111
	v_cvt_pk_bf16_f32 v110, v124, v125
	v_lshlrev_b32_e32 v124, 16, v165
	v_and_b32_e32 v125, 0xffff0000, v165
	v_and_b32_e32 v129, 0xffff0000, v111
	v_pk_mul_f32 v[128:129], v[2:3], v[128:129] op_sel_hi:[0,1]
	v_pk_mul_f32 v[128:129], v[104:105], v[128:129]
	v_lshlrev_b32_e32 v170, 16, v156
	v_and_b32_e32 v171, 0xffff0000, v156
	v_pk_mul_f32 v[124:125], v[124:125], v[128:129]
	v_lshlrev_b32_e32 v128, 16, v112
	v_cvt_pk_bf16_f32 v111, v124, v125
	v_lshlrev_b32_e32 v124, 16, v160
	v_and_b32_e32 v125, 0xffff0000, v160
	v_and_b32_e32 v129, 0xffff0000, v112
	v_pk_mul_f32 v[128:129], v[2:3], v[128:129] op_sel_hi:[0,1]
	v_pk_mul_f32 v[128:129], v[106:107], v[128:129]
	v_lshlrev_b32_e32 v160, 16, v158
	s_nop 0
	v_pk_mul_f32 v[124:125], v[124:125], v[128:129]
	v_lshlrev_b32_e32 v128, 16, v113
	v_cvt_pk_bf16_f32 v112, v124, v125
	v_lshlrev_b32_e32 v124, 16, v161
	v_and_b32_e32 v125, 0xffff0000, v161
	v_and_b32_e32 v129, 0xffff0000, v113
	v_pk_mul_f32 v[128:129], v[2:3], v[128:129] op_sel_hi:[0,1]
	v_pk_mul_f32 v[128:129], v[108:109], v[128:129]
	v_and_b32_e32 v161, 0xffff0000, v158
	v_pk_mul_f32 v[124:125], v[124:125], v[128:129]
	ds_read2_b32 v[128:129], v205 offset0:32 offset1:48
	ds_read2_b32 v[130:131], v205 offset0:160 offset1:176
	ds_read2_b32 v[132:133], v205 offset0:96 offset1:112
	ds_read2_b32 v[134:135], v205 offset0:224 offset1:240
	v_cvt_pk_bf16_f32 v113, v124, v125
	v_add_u32_e32 v124, 16, v4
	v_ashrrev_i32_e32 v125, 31, v124
	v_lshlrev_b64 v[124:125], 11, v[124:125]
	v_lshl_add_u64 v[124:125], v[150:151], 0, v[124:125]
	v_mov_b64_e32 v[58:59], v[110:111]
	v_mov_b64_e32 v[60:61], v[112:113]
	v_mov_b64_e32 v[62:63], v[124:125]
	v_add_u32_e32 v2, v204, v190
	s_waitcnt lgkmcnt(3)
	v_mov_b32_e32 v110, v128
	s_waitcnt lgkmcnt(2)
	v_mov_b32_e32 v111, v130
	s_waitcnt lgkmcnt(1)
	v_mov_b32_e32 v112, v132
	s_waitcnt lgkmcnt(0)
	v_mov_b32_e32 v113, v134
	v_pk_add_f32 v[136:137], v[110:111], v[112:113]
	ds_read_b128 v[110:113], v2
	v_add_u32_e32 v2, v204, v192
	v_lshlrev_b32_e32 v158, 16, v159
	ds_read_b128 v[124:127], v2
	v_and_b32_e32 v159, 0xffff0000, v159
	v_lshlrev_b32_e32 v204, 16, v157
	v_and_b32_e32 v205, 0xffff0000, v157
	s_waitcnt lgkmcnt(1)
	v_lshlrev_b32_e32 v164, 16, v112
	v_and_b32_e32 v165, 0xffff0000, v112
	v_mov_b32_e32 v130, v129
	v_mov_b32_e32 v134, v133
	v_pk_add_f32 v[130:131], v[130:131], v[134:135]
	v_mov_b32_e32 v133, v136
	v_mov_b32_e32 v132, v130
	v_mov_b32_e32 v136, v131
	v_pk_add_f32 v[130:131], v[132:133], v[136:137]
	v_pk_fma_f32 v[122:123], v[130:131], s[14:15], v[122:123] op_sel_hi:[1,0,0]
	v_mul_f32_e32 v2, 0x4b800000, v123
	v_cmp_gt_f32_e32 vcc, s51, v123
	v_lshlrev_b32_e32 v168, 16, v110
	v_and_b32_e32 v169, 0xffff0000, v110
	v_cndmask_b32_e32 v2, v123, v2, vcc
	v_rsq_f32_e32 v2, v2
	v_lshlrev_b32_e32 v110, 16, v111
	v_and_b32_e32 v111, 0xffff0000, v111
	v_lshlrev_b32_e32 v112, 16, v113
	v_mul_f32_e32 v5, 0x45800000, v2
	v_cndmask_b32_e32 v2, v2, v5, vcc
	v_pk_mul_f32 v[130:131], v[2:3], v[168:169] op_sel_hi:[0,1]
	v_pk_mul_f32 v[110:111], v[2:3], v[110:111] op_sel_hi:[0,1]
	v_pk_mul_f32 v[102:103], v[102:103], v[130:131]
	v_pk_mul_f32 v[104:105], v[104:105], v[110:111]
	v_pk_mul_f32 v[102:103], v[160:161], v[102:103]
	v_pk_mul_f32 v[104:105], v[158:159], v[104:105]
	v_and_b32_e32 v113, 0xffff0000, v113
	v_cvt_pk_bf16_f32 v102, v102, v103
	v_cvt_pk_bf16_f32 v103, v104, v105
	v_pk_mul_f32 v[104:105], v[2:3], v[164:165] op_sel_hi:[0,1]
	v_pk_mul_f32 v[104:105], v[106:107], v[104:105]
	v_pk_mul_f32 v[106:107], v[2:3], v[112:113] op_sel_hi:[0,1]
	v_mul_f32_e32 v2, 0x4b800000, v122
	v_cmp_gt_f32_e32 vcc, s51, v122
	v_add_u32_e32 v128, 32, v4
	v_mov_b64_e32 v[156:157], v[170:171]
	v_cndmask_b32_e32 v2, v122, v2, vcc
	v_rsq_f32_e32 v2, v2
	v_mov_b64_e32 v[170:171], v[204:205]
	v_ashrrev_i32_e32 v129, 31, v128
	v_pk_mul_f32 v[106:107], v[108:109], v[106:107]
	v_lshlrev_b64 v[128:129], 11, v[128:129]
	v_pk_mul_f32 v[104:105], v[156:157], v[104:105]
	v_pk_mul_f32 v[106:107], v[170:171], v[106:107]
	v_lshl_add_u64 v[128:129], v[150:151], 0, v[128:129]
	v_cvt_pk_bf16_f32 v104, v104, v105
	v_cvt_pk_bf16_f32 v105, v106, v107
	v_mov_b64_e32 v[64:65], v[102:103]
	v_mov_b64_e32 v[66:67], v[104:105]
	v_mov_b64_e32 v[68:69], v[128:129]
	v_mul_f32_e32 v5, 0x45800000, v2
	v_cndmask_b32_e32 v2, v2, v5, vcc
	v_lshlrev_b32_e32 v102, 16, v154
	v_and_b32_e32 v103, 0xffff0000, v154
	s_waitcnt lgkmcnt(0)
	v_lshlrev_b32_e32 v106, 16, v124
	v_and_b32_e32 v107, 0xffff0000, v124
	v_pk_mul_f32 v[106:107], v[2:3], v[106:107] op_sel_hi:[0,1]
	v_pk_mul_f32 v[106:107], v[118:119], v[106:107]
	v_lshlrev_b32_e32 v104, 16, v155
	v_pk_mul_f32 v[102:103], v[102:103], v[106:107]
	v_and_b32_e32 v105, 0xffff0000, v155
	v_cvt_pk_bf16_f32 v102, v102, v103
	v_lshlrev_b32_e32 v108, 16, v125
	v_and_b32_e32 v109, 0xffff0000, v125
	v_pk_mul_f32 v[108:109], v[2:3], v[108:109] op_sel_hi:[0,1]
	v_pk_mul_f32 v[108:109], v[120:121], v[108:109]
	v_lshlrev_b32_e32 v110, 16, v127
	v_pk_mul_f32 v[104:105], v[104:105], v[108:109]
	v_lshlrev_b32_e32 v108, 16, v126
	v_cvt_pk_bf16_f32 v103, v104, v105
	v_lshlrev_b32_e32 v104, 16, v152
	v_and_b32_e32 v105, 0xffff0000, v152
	v_and_b32_e32 v109, 0xffff0000, v126
	v_pk_mul_f32 v[108:109], v[2:3], v[108:109] op_sel_hi:[0,1]
	v_pk_mul_f32 v[108:109], v[114:115], v[108:109]
	v_and_b32_e32 v111, 0xffff0000, v127
	v_lshlrev_b32_e32 v106, 16, v153
	v_pk_mul_f32 v[104:105], v[104:105], v[108:109]
	v_and_b32_e32 v107, 0xffff0000, v153
	v_cvt_pk_bf16_f32 v104, v104, v105
	v_pk_mul_f32 v[110:111], v[2:3], v[110:111] op_sel_hi:[0,1]
	v_add_u32_e32 v4, 48, v4
	v_pk_mul_f32 v[110:111], v[116:117], v[110:111]
	v_ashrrev_i32_e32 v5, 31, v4
	v_lshlrev_b64 v[4:5], 11, v[4:5]
	v_pk_mul_f32 v[106:107], v[106:107], v[110:111]
	v_lshl_add_u64 v[4:5], v[150:151], 0, v[4:5]
	v_cvt_pk_bf16_f32 v105, v106, v107
	v_mov_b64_e32 v[70:71], v[102:103]
	v_mov_b64_e32 v[72:73], v[104:105]
	v_mov_b64_e32 v[74:75], v[4:5]
	s_branch .Lfin_partB

.Lfin_partB:
	s_and_b64 s[0:1], s[24:25], exec
	s_cselect_b32 s0, s31, s29
	s_mul_hi_u32 s1, s26, s0
	s_mul_i32 s0, s26, s0
	v_lshl_add_u64 v[4:5], s[0:1], 1, v[162:163]
	s_mov_b32 s29, s9
	v_lshl_add_u64 v[102:103], v[4:5], 0, s[8:9]
	v_lshl_add_u64 v[104:105], v[4:5], 0, s[28:29]
	s_mov_b32 s37, s9
	s_mov_b32 s31, s9
	v_lshl_add_u64 v[106:107], v[104:105], 0, s[8:9]
	global_load_dwordx2 v[170:171], v[4:5], off
	global_load_dwordx2 v[168:169], v[102:103], off
	global_load_dwordx2 v[164:165], v[104:105], off
	global_load_dwordx2 v[160:161], v[106:107], off
	v_lshl_add_u64 v[102:103], v[4:5], 0, s[36:37]
	v_lshl_add_u64 v[4:5], v[4:5], 0, s[30:31]
	v_lshl_add_u64 v[104:105], v[102:103], 0, s[8:9]
	v_lshl_add_u64 v[106:107], v[4:5], 0, s[8:9]
	global_load_dwordx2 v[158:159], v[102:103], off
	global_load_dwordx2 v[156:157], v[104:105], off
	global_load_dwordx2 v[154:155], v[4:5], off
	global_load_dwordx2 v[152:153], v[106:107], off
	s_and_b64 vcc, exec, s[6:7]
	s_cbranch_vccnz .Lfin_stores
	s_lshl_b64 s[0:1], s[38:39], 2
	s_add_u32 s0, s41, s0
	s_addc_u32 s1, s42, s1
	global_load_dword v147, v3, s[0:1]
	s_branch .LBB0_447
